# GQA attention loop: the earlier deep K-fragment LDS prefetch removed again (placement-matched probes show it cost ~12 us per attention phase); waits re-derived per consumer
# speedup vs baseline: 1.2879x; 1.0039x over previous
; __device__ __forceinline__ int crow(int r, int hi) { return (r & 3) + 8 * (r >> 2) + 4 * hi; }
; __device__ __forceinline__ unsigned cvtpk(float lo, float hi) { unsigned r; asm volatile("v_cvt_pk_bf16_f32 %0, %1, %2" : "=v"(r) : "v"(lo), "v"(hi)); return r; }
; template <int DKR, int LDQ, int LDK, int LDV, int LDO> ...
;     ...
;   if (hi == 0) li_l[r32] = l_reg; asm volatile("s_waitcnt lgkmcnt(0)" ::: "memory");
;   float rli[16];
; #pragma unroll
;   for (int r = 0; r < 16; ++r) rli[r] = __builtin_amdgcn_rcpf(li_l[crow(r, hi)]);
;   bf16_t* Ow = Ob + (long)(wid * QBLK) * LDO;
; #pragma unroll
;   for (int r = 0; r < 16; ++r) { int orow = crow(r, hi);
; #pragma unroll
;     for (int d0 = 0; d0 < 4; ++d0) Ow[(long)orow * LDO + d0 * 32 + r32] = (bf16_t)(cvtpk(o[d0][r] * rli[r], 0.f) & 0xffffu); }
.LBB0_595:
	s_or_b64 exec, exec, s[0:1]
	s_waitcnt lgkmcnt(0)
	v_add_u32_e32 v72, v135, v132
	ds_read_b128 v[68:71], v72
	ds_read_b128 v[74:77], v72 offset:32
	ds_read_b128 v[78:81], v72 offset:64
	ds_read_b128 v[82:85], v72 offset:96
	s_add_u32 s0, s29, s36
	v_ashrrev_i32_e32 v135, 31, v134
	s_addc_u32 s1, s40, s37
	v_lshlrev_b64 v[64:65], 12, v[134:135]
	v_lshl_add_u64 v[64:65], s[0:1], 0, v[64:65]
	v_lshlrev_b32_e32 v132, 1, v145
	v_lshlrev_b32_e32 v66, 14, v146
	v_lshl_add_u64 v[64:65], v[64:65], 0, v[132:133]
	v_mov_b32_e32 v67, v133
	v_lshl_add_u64 v[64:65], v[64:65], 0, v[66:67]
	v_mbcnt_lo_u32_b32 v90, -1, 0
	v_mbcnt_hi_u32_b32 v90, -1, v90
	v_and_b32_e32 v90, 1, v90
	v_mul_u32_u24_e32 v90, 0xffe, v90
	v_mov_b32_e32 v91, 0
	v_lshl_add_u64 v[86:87], v[64:65], 0, v[90:91]
	s_waitcnt lgkmcnt(0)
	v_rcp_f32_e32 v68, v68
	v_rcp_f32_e32 v69, v69
	v_rcp_f32_e32 v70, v70
	v_rcp_f32_e32 v71, v71
	v_rcp_f32_e32 v74, v74
	v_rcp_f32_e32 v75, v75
	v_rcp_f32_e32 v76, v76
	v_rcp_f32_e32 v77, v77
	v_rcp_f32_e32 v78, v78
	v_rcp_f32_e32 v79, v79
	v_rcp_f32_e32 v80, v80
	v_rcp_f32_e32 v81, v81
	v_rcp_f32_e32 v82, v82
	v_rcp_f32_e32 v83, v83
	v_rcp_f32_e32 v84, v84
	v_rcp_f32_e32 v85, v85
	s_mov_b32 vcc_lo, 0xaaaaaaaa
	s_mov_b32 vcc_hi, 0xaaaaaaaa
	s_nop 1
	v_cndmask_b32_e32 v92, v68, v69, vcc
	v_cndmask_b32_e32 v94, v70, v71, vcc
	v_cndmask_b32_e32 v96, v74, v75, vcc
	v_cndmask_b32_e32 v98, v76, v77, vcc
	v_cndmask_b32_e32 v100, v78, v79, vcc
	v_cndmask_b32_e32 v102, v80, v81, vcc
	v_cndmask_b32_e32 v104, v82, v83, vcc
	v_cndmask_b32_e32 v106, v84, v85, vcc
	v_lshl_add_u64 v[88:89], v[86:87], 0, 0
	s_mov_b32 vcc_lo, 0x55555555
	s_mov_b32 vcc_hi, 0x55555555
	s_nop 1
	v_cndmask_b32_dpp v108, v1, v0, vcc quad_perm:[1,0,3,2] row_mask:0xf bank_mask:0xf
	v_cndmask_b32_dpp v110, v49, v48, vcc quad_perm:[1,0,3,2] row_mask:0xf bank_mask:0xf
	v_cndmask_b32_dpp v112, v33, v32, vcc quad_perm:[1,0,3,2] row_mask:0xf bank_mask:0xf
	v_cndmask_b32_dpp v114, v17, v16, vcc quad_perm:[1,0,3,2] row_mask:0xf bank_mask:0xf
	s_mov_b32 vcc_lo, 0xaaaaaaaa
	s_mov_b32 vcc_hi, 0xaaaaaaaa
	s_nop 1
	v_cndmask_b32_dpp v109, v0, v1, vcc quad_perm:[1,0,3,2] row_mask:0xf bank_mask:0xf
	v_cndmask_b32_dpp v111, v48, v49, vcc quad_perm:[1,0,3,2] row_mask:0xf bank_mask:0xf
	v_cndmask_b32_dpp v113, v32, v33, vcc quad_perm:[1,0,3,2] row_mask:0xf bank_mask:0xf
	v_cndmask_b32_dpp v115, v16, v17, vcc quad_perm:[1,0,3,2] row_mask:0xf bank_mask:0xf
	v_pk_mul_f32 v[108:109], v[108:109], v[92:93] op_sel_hi:[1,0]
	v_pk_mul_f32 v[110:111], v[110:111], v[92:93] op_sel_hi:[1,0]
	v_pk_mul_f32 v[112:113], v[112:113], v[92:93] op_sel_hi:[1,0]
	v_pk_mul_f32 v[114:115], v[114:115], v[92:93] op_sel_hi:[1,0]
	v_cvt_pk_bf16_f32 v73, v108, v109
	v_cvt_pk_bf16_f32 v116, v110, v111
	v_cvt_pk_bf16_f32 v117, v112, v113
	v_cvt_pk_bf16_f32 v118, v114, v115
	global_store_dword v[88:89], v73, off
	global_store_dword v[88:89], v116, off offset:64
	global_store_dword v[88:89], v117, off offset:128
	global_store_dword v[88:89], v118, off offset:192
	s_mov_b64 s[0:1], 0x2000
	v_lshl_add_u64 v[88:89], v[86:87], 0, s[0:1]
	s_mov_b32 vcc_lo, 0x55555555
	s_mov_b32 vcc_hi, 0x55555555
	s_nop 1
	v_cndmask_b32_dpp v108, v3, v2, vcc quad_perm:[1,0,3,2] row_mask:0xf bank_mask:0xf
	v_cndmask_b32_dpp v110, v51, v50, vcc quad_perm:[1,0,3,2] row_mask:0xf bank_mask:0xf
	v_cndmask_b32_dpp v112, v35, v34, vcc quad_perm:[1,0,3,2] row_mask:0xf bank_mask:0xf
	v_cndmask_b32_dpp v114, v19, v18, vcc quad_perm:[1,0,3,2] row_mask:0xf bank_mask:0xf
	s_mov_b32 vcc_lo, 0xaaaaaaaa
	s_mov_b32 vcc_hi, 0xaaaaaaaa
	s_nop 1
	v_cndmask_b32_dpp v109, v2, v3, vcc quad_perm:[1,0,3,2] row_mask:0xf bank_mask:0xf
	v_cndmask_b32_dpp v111, v50, v51, vcc quad_perm:[1,0,3,2] row_mask:0xf bank_mask:0xf
	v_cndmask_b32_dpp v113, v34, v35, vcc quad_perm:[1,0,3,2] row_mask:0xf bank_mask:0xf
	v_cndmask_b32_dpp v115, v18, v19, vcc quad_perm:[1,0,3,2] row_mask:0xf bank_mask:0xf
	v_pk_mul_f32 v[108:109], v[108:109], v[94:95] op_sel_hi:[1,0]
	v_pk_mul_f32 v[110:111], v[110:111], v[94:95] op_sel_hi:[1,0]
	v_pk_mul_f32 v[112:113], v[112:113], v[94:95] op_sel_hi:[1,0]
	v_pk_mul_f32 v[114:115], v[114:115], v[94:95] op_sel_hi:[1,0]
	v_cvt_pk_bf16_f32 v73, v108, v109
	v_cvt_pk_bf16_f32 v116, v110, v111
	v_cvt_pk_bf16_f32 v117, v112, v113
	v_cvt_pk_bf16_f32 v118, v114, v115
	global_store_dword v[88:89], v73, off
	global_store_dword v[88:89], v116, off offset:64
	global_store_dword v[88:89], v117, off offset:128
	global_store_dword v[88:89], v118, off offset:192
	s_mov_b64 s[0:1], 0x8000
	v_lshl_add_u64 v[88:89], v[86:87], 0, s[0:1]
	s_mov_b32 vcc_lo, 0x55555555
	s_mov_b32 vcc_hi, 0x55555555
	s_nop 1
	v_cndmask_b32_dpp v108, v5, v4, vcc quad_perm:[1,0,3,2] row_mask:0xf bank_mask:0xf
	v_cndmask_b32_dpp v110, v53, v52, vcc quad_perm:[1,0,3,2] row_mask:0xf bank_mask:0xf
	v_cndmask_b32_dpp v112, v37, v36, vcc quad_perm:[1,0,3,2] row_mask:0xf bank_mask:0xf
	v_cndmask_b32_dpp v114, v21, v20, vcc quad_perm:[1,0,3,2] row_mask:0xf bank_mask:0xf
	s_mov_b32 vcc_lo, 0xaaaaaaaa
	s_mov_b32 vcc_hi, 0xaaaaaaaa
	s_nop 1
	v_cndmask_b32_dpp v109, v4, v5, vcc quad_perm:[1,0,3,2] row_mask:0xf bank_mask:0xf
	v_cndmask_b32_dpp v111, v52, v53, vcc quad_perm:[1,0,3,2] row_mask:0xf bank_mask:0xf
	v_cndmask_b32_dpp v113, v36, v37, vcc quad_perm:[1,0,3,2] row_mask:0xf bank_mask:0xf
	v_cndmask_b32_dpp v115, v20, v21, vcc quad_perm:[1,0,3,2] row_mask:0xf bank_mask:0xf
	v_pk_mul_f32 v[108:109], v[108:109], v[96:97] op_sel_hi:[1,0]
	v_pk_mul_f32 v[110:111], v[110:111], v[96:97] op_sel_hi:[1,0]
	v_pk_mul_f32 v[112:113], v[112:113], v[96:97] op_sel_hi:[1,0]
	v_pk_mul_f32 v[114:115], v[114:115], v[96:97] op_sel_hi:[1,0]
; __device__ __forceinline__ int crow(int r, int hi) { return (r & 3) + 8 * (r >> 2) + 4 * hi; }
; __device__ __forceinline__ unsigned cvtpk(float lo, float hi) { unsigned r; asm volatile("v_cvt_pk_bf16_f32 %0, %1, %2" : "=v"(r) : "v"(lo), "v"(hi)); return r; }
; template <int DKR, int LDQ, int LDK, int LDV, int LDO> ...
;     ...
;   for (int r = 0; r < 16; ++r) { int orow = crow(r, hi);
; #pragma unroll
;     for (int d0 = 0; d0 < 4; ++d0) Ow[(long)orow * LDO + d0 * 32 + r32] = (bf16_t)(cvtpk(o[d0][r] * rli[r], 0.f) & 0xffffu); }
	v_cvt_pk_bf16_f32 v73, v108, v109
	v_cvt_pk_bf16_f32 v116, v110, v111
	v_cvt_pk_bf16_f32 v117, v112, v113
	v_cvt_pk_bf16_f32 v118, v114, v115
	global_store_dword v[88:89], v73, off
	global_store_dword v[88:89], v116, off offset:64
	global_store_dword v[88:89], v117, off offset:128
	global_store_dword v[88:89], v118, off offset:192
	s_mov_b64 s[0:1], 0xa000
	v_lshl_add_u64 v[88:89], v[86:87], 0, s[0:1]
	s_mov_b32 vcc_lo, 0x55555555
	s_mov_b32 vcc_hi, 0x55555555
	s_nop 1
	v_cndmask_b32_dpp v108, v7, v6, vcc quad_perm:[1,0,3,2] row_mask:0xf bank_mask:0xf
	v_cndmask_b32_dpp v110, v55, v54, vcc quad_perm:[1,0,3,2] row_mask:0xf bank_mask:0xf
	v_cndmask_b32_dpp v112, v39, v38, vcc quad_perm:[1,0,3,2] row_mask:0xf bank_mask:0xf
	v_cndmask_b32_dpp v114, v23, v22, vcc quad_perm:[1,0,3,2] row_mask:0xf bank_mask:0xf
	s_mov_b32 vcc_lo, 0xaaaaaaaa
	s_mov_b32 vcc_hi, 0xaaaaaaaa
	s_nop 1
	v_cndmask_b32_dpp v109, v6, v7, vcc quad_perm:[1,0,3,2] row_mask:0xf bank_mask:0xf
	v_cndmask_b32_dpp v111, v54, v55, vcc quad_perm:[1,0,3,2] row_mask:0xf bank_mask:0xf
	v_cndmask_b32_dpp v113, v38, v39, vcc quad_perm:[1,0,3,2] row_mask:0xf bank_mask:0xf
	v_cndmask_b32_dpp v115, v22, v23, vcc quad_perm:[1,0,3,2] row_mask:0xf bank_mask:0xf
	v_pk_mul_f32 v[108:109], v[108:109], v[98:99] op_sel_hi:[1,0]
	v_pk_mul_f32 v[110:111], v[110:111], v[98:99] op_sel_hi:[1,0]
	v_pk_mul_f32 v[112:113], v[112:113], v[98:99] op_sel_hi:[1,0]
	v_pk_mul_f32 v[114:115], v[114:115], v[98:99] op_sel_hi:[1,0]
	v_cvt_pk_bf16_f32 v73, v108, v109
	v_cvt_pk_bf16_f32 v116, v110, v111
	v_cvt_pk_bf16_f32 v117, v112, v113
	v_cvt_pk_bf16_f32 v118, v114, v115
	global_store_dword v[88:89], v73, off
	global_store_dword v[88:89], v116, off offset:64
	global_store_dword v[88:89], v117, off offset:128
	global_store_dword v[88:89], v118, off offset:192
	s_mov_b64 s[0:1], 0x10000
	v_lshl_add_u64 v[88:89], v[86:87], 0, s[0:1]
	s_mov_b32 vcc_lo, 0x55555555
	s_mov_b32 vcc_hi, 0x55555555
	s_nop 1
	v_cndmask_b32_dpp v108, v9, v8, vcc quad_perm:[1,0,3,2] row_mask:0xf bank_mask:0xf
	v_cndmask_b32_dpp v110, v57, v56, vcc quad_perm:[1,0,3,2] row_mask:0xf bank_mask:0xf
	v_cndmask_b32_dpp v112, v41, v40, vcc quad_perm:[1,0,3,2] row_mask:0xf bank_mask:0xf
	v_cndmask_b32_dpp v114, v25, v24, vcc quad_perm:[1,0,3,2] row_mask:0xf bank_mask:0xf
	s_mov_b32 vcc_lo, 0xaaaaaaaa
	s_mov_b32 vcc_hi, 0xaaaaaaaa
	s_nop 1
	v_cndmask_b32_dpp v109, v8, v9, vcc quad_perm:[1,0,3,2] row_mask:0xf bank_mask:0xf
	v_cndmask_b32_dpp v111, v56, v57, vcc quad_perm:[1,0,3,2] row_mask:0xf bank_mask:0xf
	v_cndmask_b32_dpp v113, v40, v41, vcc quad_perm:[1,0,3,2] row_mask:0xf bank_mask:0xf
	v_cndmask_b32_dpp v115, v24, v25, vcc quad_perm:[1,0,3,2] row_mask:0xf bank_mask:0xf
	v_pk_mul_f32 v[108:109], v[108:109], v[100:101] op_sel_hi:[1,0]
	v_pk_mul_f32 v[110:111], v[110:111], v[100:101] op_sel_hi:[1,0]
	v_pk_mul_f32 v[112:113], v[112:113], v[100:101] op_sel_hi:[1,0]
	v_pk_mul_f32 v[114:115], v[114:115], v[100:101] op_sel_hi:[1,0]
	v_cvt_pk_bf16_f32 v73, v108, v109
	v_cvt_pk_bf16_f32 v116, v110, v111
	v_cvt_pk_bf16_f32 v117, v112, v113
	v_cvt_pk_bf16_f32 v118, v114, v115
	global_store_dword v[88:89], v73, off
	global_store_dword v[88:89], v116, off offset:64
	global_store_dword v[88:89], v117, off offset:128
	global_store_dword v[88:89], v118, off offset:192
	s_mov_b64 s[0:1], 0x12000
	v_lshl_add_u64 v[88:89], v[86:87], 0, s[0:1]
	s_mov_b32 vcc_lo, 0x55555555
	s_mov_b32 vcc_hi, 0x55555555
	s_nop 1
	v_cndmask_b32_dpp v108, v11, v10, vcc quad_perm:[1,0,3,2] row_mask:0xf bank_mask:0xf
	v_cndmask_b32_dpp v110, v59, v58, vcc quad_perm:[1,0,3,2] row_mask:0xf bank_mask:0xf
	v_cndmask_b32_dpp v112, v43, v42, vcc quad_perm:[1,0,3,2] row_mask:0xf bank_mask:0xf
	v_cndmask_b32_dpp v114, v27, v26, vcc quad_perm:[1,0,3,2] row_mask:0xf bank_mask:0xf
	s_mov_b32 vcc_lo, 0xaaaaaaaa
	s_mov_b32 vcc_hi, 0xaaaaaaaa
	s_nop 1
	v_cndmask_b32_dpp v109, v10, v11, vcc quad_perm:[1,0,3,2] row_mask:0xf bank_mask:0xf
; __device__ __forceinline__ int crow(int r, int hi) { return (r & 3) + 8 * (r >> 2) + 4 * hi; }
; __device__ __forceinline__ unsigned cvtpk(float lo, float hi) { unsigned r; asm volatile("v_cvt_pk_bf16_f32 %0, %1, %2" : "=v"(r) : "v"(lo), "v"(hi)); return r; }
; template <int DKR, int LDQ, int LDK, int LDV, int LDO> ...
;     ...
;   for (int r = 0; r < 16; ++r) { int orow = crow(r, hi);
; #pragma unroll
;     for (int d0 = 0; d0 < 4; ++d0) Ow[(long)orow * LDO + d0 * 32 + r32] = (bf16_t)(cvtpk(o[d0][r] * rli[r], 0.f) & 0xffffu); }
;   __syncthreads();
	v_cndmask_b32_dpp v111, v58, v59, vcc quad_perm:[1,0,3,2] row_mask:0xf bank_mask:0xf
	v_cndmask_b32_dpp v113, v42, v43, vcc quad_perm:[1,0,3,2] row_mask:0xf bank_mask:0xf
	v_cndmask_b32_dpp v115, v26, v27, vcc quad_perm:[1,0,3,2] row_mask:0xf bank_mask:0xf
	v_pk_mul_f32 v[108:109], v[108:109], v[102:103] op_sel_hi:[1,0]
	v_pk_mul_f32 v[110:111], v[110:111], v[102:103] op_sel_hi:[1,0]
	v_pk_mul_f32 v[112:113], v[112:113], v[102:103] op_sel_hi:[1,0]
	v_pk_mul_f32 v[114:115], v[114:115], v[102:103] op_sel_hi:[1,0]
	v_cvt_pk_bf16_f32 v73, v108, v109
	v_cvt_pk_bf16_f32 v116, v110, v111
	v_cvt_pk_bf16_f32 v117, v112, v113
	v_cvt_pk_bf16_f32 v118, v114, v115
	global_store_dword v[88:89], v73, off
	global_store_dword v[88:89], v116, off offset:64
	global_store_dword v[88:89], v117, off offset:128
	global_store_dword v[88:89], v118, off offset:192
	s_mov_b64 s[0:1], 0x18000
	v_lshl_add_u64 v[88:89], v[86:87], 0, s[0:1]
	s_mov_b32 vcc_lo, 0x55555555
	s_mov_b32 vcc_hi, 0x55555555
	s_nop 1
	v_cndmask_b32_dpp v108, v13, v12, vcc quad_perm:[1,0,3,2] row_mask:0xf bank_mask:0xf
	v_cndmask_b32_dpp v110, v61, v60, vcc quad_perm:[1,0,3,2] row_mask:0xf bank_mask:0xf
	v_cndmask_b32_dpp v112, v45, v44, vcc quad_perm:[1,0,3,2] row_mask:0xf bank_mask:0xf
	v_cndmask_b32_dpp v114, v29, v28, vcc quad_perm:[1,0,3,2] row_mask:0xf bank_mask:0xf
	s_mov_b32 vcc_lo, 0xaaaaaaaa
	s_mov_b32 vcc_hi, 0xaaaaaaaa
	s_nop 1
	v_cndmask_b32_dpp v109, v12, v13, vcc quad_perm:[1,0,3,2] row_mask:0xf bank_mask:0xf
	v_cndmask_b32_dpp v111, v60, v61, vcc quad_perm:[1,0,3,2] row_mask:0xf bank_mask:0xf
	v_cndmask_b32_dpp v113, v44, v45, vcc quad_perm:[1,0,3,2] row_mask:0xf bank_mask:0xf
	v_cndmask_b32_dpp v115, v28, v29, vcc quad_perm:[1,0,3,2] row_mask:0xf bank_mask:0xf
	v_pk_mul_f32 v[108:109], v[108:109], v[104:105] op_sel_hi:[1,0]
	v_pk_mul_f32 v[110:111], v[110:111], v[104:105] op_sel_hi:[1,0]
	v_pk_mul_f32 v[112:113], v[112:113], v[104:105] op_sel_hi:[1,0]
	v_pk_mul_f32 v[114:115], v[114:115], v[104:105] op_sel_hi:[1,0]
	v_cvt_pk_bf16_f32 v73, v108, v109
	v_cvt_pk_bf16_f32 v116, v110, v111
	v_cvt_pk_bf16_f32 v117, v112, v113
	v_cvt_pk_bf16_f32 v118, v114, v115
	global_store_dword v[88:89], v73, off
	global_store_dword v[88:89], v116, off offset:64
	global_store_dword v[88:89], v117, off offset:128
	global_store_dword v[88:89], v118, off offset:192
	s_mov_b64 s[0:1], 0x1a000
	v_lshl_add_u64 v[88:89], v[86:87], 0, s[0:1]
	s_mov_b32 vcc_lo, 0x55555555
	s_mov_b32 vcc_hi, 0x55555555
	s_nop 1
	v_cndmask_b32_dpp v108, v15, v14, vcc quad_perm:[1,0,3,2] row_mask:0xf bank_mask:0xf
	v_cndmask_b32_dpp v110, v63, v62, vcc quad_perm:[1,0,3,2] row_mask:0xf bank_mask:0xf
	v_cndmask_b32_dpp v112, v47, v46, vcc quad_perm:[1,0,3,2] row_mask:0xf bank_mask:0xf
	v_cndmask_b32_dpp v114, v31, v30, vcc quad_perm:[1,0,3,2] row_mask:0xf bank_mask:0xf
	s_mov_b32 vcc_lo, 0xaaaaaaaa
	s_mov_b32 vcc_hi, 0xaaaaaaaa
	s_nop 1
	v_cndmask_b32_dpp v109, v14, v15, vcc quad_perm:[1,0,3,2] row_mask:0xf bank_mask:0xf
	v_cndmask_b32_dpp v111, v62, v63, vcc quad_perm:[1,0,3,2] row_mask:0xf bank_mask:0xf
	v_cndmask_b32_dpp v113, v46, v47, vcc quad_perm:[1,0,3,2] row_mask:0xf bank_mask:0xf
	v_cndmask_b32_dpp v115, v30, v31, vcc quad_perm:[1,0,3,2] row_mask:0xf bank_mask:0xf
	v_pk_mul_f32 v[108:109], v[108:109], v[106:107] op_sel_hi:[1,0]
	v_pk_mul_f32 v[110:111], v[110:111], v[106:107] op_sel_hi:[1,0]
	v_pk_mul_f32 v[112:113], v[112:113], v[106:107] op_sel_hi:[1,0]
	v_pk_mul_f32 v[114:115], v[114:115], v[106:107] op_sel_hi:[1,0]
	v_cvt_pk_bf16_f32 v73, v108, v109
	v_cvt_pk_bf16_f32 v116, v110, v111
	v_cvt_pk_bf16_f32 v117, v112, v113
	v_cvt_pk_bf16_f32 v118, v114, v115
	global_store_dword v[88:89], v73, off
	global_store_dword v[88:89], v116, off offset:64
	global_store_dword v[88:89], v117, off offset:128
	global_store_dword v[88:89], v118, off offset:192
	s_mov_b32 s2, 4
	s_andn2_b64 vcc, exec, s[14:15]
	s_mov_b64 s[0:1], 0
	s_waitcnt vmcnt(63) expcnt(7) lgkmcnt(15)
	s_barrier
	s_cbranch_vccz .LBB0_613
	s_nop 0
	s_nop 0
	s_nop 0
	s_nop 0

; __device__ __forceinline__ int crow(int r, int hi) { return (r & 3) + 8 * (r >> 2) + 4 * hi; }
; __device__ __forceinline__ unsigned cvtpk(float lo, float hi) { unsigned r; asm volatile("v_cvt_pk_bf16_f32 %0, %1, %2" : "=v"(r) : "v"(lo), "v"(hi)); return r; }
; template <int DKR, int LDQ, int LDK, int LDV, int LDO> ...
;     ...
;   if (hi == 0) li_l[r32] = l_reg; asm volatile("s_waitcnt lgkmcnt(0)" ::: "memory");
;   float rli[16];
; #pragma unroll
;   for (int r = 0; r < 16; ++r) rli[r] = __builtin_amdgcn_rcpf(li_l[crow(r, hi)]);
;   bf16_t* Ow = Ob + (long)(wid * QBLK) * LDO;
; #pragma unroll
;   for (int r = 0; r < 16; ++r) { int orow = crow(r, hi);
; #pragma unroll
;     for (int d0 = 0; d0 < 4; ++d0) Ow[(long)orow * LDO + d0 * 32 + r32] = (bf16_t)(cvtpk(o[d0][r] * rli[r], 0.f) & 0xffffu); }
.LBB0_614:
	s_or_b64 exec, exec, s[0:1]
	s_waitcnt lgkmcnt(0)
	v_add_u32_e32 v72, v179, v176
	ds_read_b128 v[68:71], v72
	ds_read_b128 v[74:77], v72 offset:32
	ds_read_b128 v[78:81], v72 offset:64
	ds_read_b128 v[82:85], v72 offset:96
	s_add_u32 s0, s29, s12
	v_ashrrev_i32_e32 v179, 31, v178
	s_addc_u32 s1, s40, s13
	v_lshlrev_b64 v[64:65], 12, v[178:179]
	v_lshl_add_u64 v[64:65], s[0:1], 0, v[64:65]
	v_lshlrev_b32_e32 v176, 1, v184
	v_lshlrev_b32_e32 v66, 14, v183
	v_lshl_add_u64 v[64:65], v[64:65], 0, v[176:177]
	v_mov_b32_e32 v67, v177
	v_lshl_add_u64 v[64:65], v[64:65], 0, v[66:67]
	v_mbcnt_lo_u32_b32 v90, -1, 0
	v_mbcnt_hi_u32_b32 v90, -1, v90
	v_and_b32_e32 v90, 1, v90
	v_mul_u32_u24_e32 v90, 0xffe, v90
	v_mov_b32_e32 v91, 0
	v_lshl_add_u64 v[86:87], v[64:65], 0, v[90:91]
	s_waitcnt lgkmcnt(0)
	v_rcp_f32_e32 v68, v68
	v_rcp_f32_e32 v69, v69
	v_rcp_f32_e32 v70, v70
	v_rcp_f32_e32 v71, v71
	v_rcp_f32_e32 v74, v74
	v_rcp_f32_e32 v75, v75
	v_rcp_f32_e32 v76, v76
	v_rcp_f32_e32 v77, v77
	v_rcp_f32_e32 v78, v78
	v_rcp_f32_e32 v79, v79
	v_rcp_f32_e32 v80, v80
	v_rcp_f32_e32 v81, v81
	v_rcp_f32_e32 v82, v82
	v_rcp_f32_e32 v83, v83
	v_rcp_f32_e32 v84, v84
	v_rcp_f32_e32 v85, v85
	s_mov_b32 vcc_lo, 0xaaaaaaaa
	s_mov_b32 vcc_hi, 0xaaaaaaaa
	s_nop 1
	v_cndmask_b32_e32 v92, v68, v69, vcc
	v_cndmask_b32_e32 v94, v70, v71, vcc
	v_cndmask_b32_e32 v96, v74, v75, vcc
	v_cndmask_b32_e32 v98, v76, v77, vcc
	v_cndmask_b32_e32 v100, v78, v79, vcc
	v_cndmask_b32_e32 v102, v80, v81, vcc
	v_cndmask_b32_e32 v104, v82, v83, vcc
	v_cndmask_b32_e32 v106, v84, v85, vcc
	v_lshl_add_u64 v[88:89], v[86:87], 0, 0
	s_mov_b32 vcc_lo, 0x55555555
	s_mov_b32 vcc_hi, 0x55555555
	s_nop 1
	v_cndmask_b32_dpp v108, v1, v0, vcc quad_perm:[1,0,3,2] row_mask:0xf bank_mask:0xf
	v_cndmask_b32_dpp v110, v49, v48, vcc quad_perm:[1,0,3,2] row_mask:0xf bank_mask:0xf
	v_cndmask_b32_dpp v112, v33, v32, vcc quad_perm:[1,0,3,2] row_mask:0xf bank_mask:0xf
	v_cndmask_b32_dpp v114, v17, v16, vcc quad_perm:[1,0,3,2] row_mask:0xf bank_mask:0xf
	s_mov_b32 vcc_lo, 0xaaaaaaaa
	s_mov_b32 vcc_hi, 0xaaaaaaaa
	s_nop 1
	v_cndmask_b32_dpp v109, v0, v1, vcc quad_perm:[1,0,3,2] row_mask:0xf bank_mask:0xf
	v_cndmask_b32_dpp v111, v48, v49, vcc quad_perm:[1,0,3,2] row_mask:0xf bank_mask:0xf
	v_cndmask_b32_dpp v113, v32, v33, vcc quad_perm:[1,0,3,2] row_mask:0xf bank_mask:0xf
	v_cndmask_b32_dpp v115, v16, v17, vcc quad_perm:[1,0,3,2] row_mask:0xf bank_mask:0xf
	v_pk_mul_f32 v[108:109], v[108:109], v[92:93] op_sel_hi:[1,0]
	v_pk_mul_f32 v[110:111], v[110:111], v[92:93] op_sel_hi:[1,0]
	v_pk_mul_f32 v[112:113], v[112:113], v[92:93] op_sel_hi:[1,0]
	v_pk_mul_f32 v[114:115], v[114:115], v[92:93] op_sel_hi:[1,0]
	v_cvt_pk_bf16_f32 v73, v108, v109
	v_cvt_pk_bf16_f32 v116, v110, v111
	v_cvt_pk_bf16_f32 v117, v112, v113
	v_cvt_pk_bf16_f32 v118, v114, v115
	global_store_dword v[88:89], v73, off offset:2048
	global_store_dword v[88:89], v116, off offset:2112
	global_store_dword v[88:89], v117, off offset:2176
	global_store_dword v[88:89], v118, off offset:2240
	s_mov_b64 s[0:1], 0x2000
	v_lshl_add_u64 v[88:89], v[86:87], 0, s[0:1]
	s_mov_b32 vcc_lo, 0x55555555
	s_mov_b32 vcc_hi, 0x55555555
	s_nop 1
	v_cndmask_b32_dpp v108, v3, v2, vcc quad_perm:[1,0,3,2] row_mask:0xf bank_mask:0xf
	v_cndmask_b32_dpp v110, v51, v50, vcc quad_perm:[1,0,3,2] row_mask:0xf bank_mask:0xf
	v_cndmask_b32_dpp v112, v35, v34, vcc quad_perm:[1,0,3,2] row_mask:0xf bank_mask:0xf
	v_cndmask_b32_dpp v114, v19, v18, vcc quad_perm:[1,0,3,2] row_mask:0xf bank_mask:0xf
	s_mov_b32 vcc_lo, 0xaaaaaaaa
	s_mov_b32 vcc_hi, 0xaaaaaaaa
	s_nop 1
	v_cndmask_b32_dpp v109, v2, v3, vcc quad_perm:[1,0,3,2] row_mask:0xf bank_mask:0xf
	v_cndmask_b32_dpp v111, v50, v51, vcc quad_perm:[1,0,3,2] row_mask:0xf bank_mask:0xf
	v_cndmask_b32_dpp v113, v34, v35, vcc quad_perm:[1,0,3,2] row_mask:0xf bank_mask:0xf
	v_cndmask_b32_dpp v115, v18, v19, vcc quad_perm:[1,0,3,2] row_mask:0xf bank_mask:0xf
	v_pk_mul_f32 v[108:109], v[108:109], v[94:95] op_sel_hi:[1,0]
	v_pk_mul_f32 v[110:111], v[110:111], v[94:95] op_sel_hi:[1,0]
	v_pk_mul_f32 v[112:113], v[112:113], v[94:95] op_sel_hi:[1,0]
	v_pk_mul_f32 v[114:115], v[114:115], v[94:95] op_sel_hi:[1,0]
	v_cvt_pk_bf16_f32 v73, v108, v109
	v_cvt_pk_bf16_f32 v116, v110, v111
	v_cvt_pk_bf16_f32 v117, v112, v113
	v_cvt_pk_bf16_f32 v118, v114, v115
	global_store_dword v[88:89], v73, off offset:2048
	global_store_dword v[88:89], v116, off offset:2112
	global_store_dword v[88:89], v117, off offset:2176
	global_store_dword v[88:89], v118, off offset:2240
	s_mov_b64 s[0:1], 0x8000
	v_lshl_add_u64 v[88:89], v[86:87], 0, s[0:1]
	s_mov_b32 vcc_lo, 0x55555555
	s_mov_b32 vcc_hi, 0x55555555
	s_nop 1
	v_cndmask_b32_dpp v108, v5, v4, vcc quad_perm:[1,0,3,2] row_mask:0xf bank_mask:0xf
	v_cndmask_b32_dpp v110, v53, v52, vcc quad_perm:[1,0,3,2] row_mask:0xf bank_mask:0xf
	v_cndmask_b32_dpp v112, v37, v36, vcc quad_perm:[1,0,3,2] row_mask:0xf bank_mask:0xf
	v_cndmask_b32_dpp v114, v21, v20, vcc quad_perm:[1,0,3,2] row_mask:0xf bank_mask:0xf
	s_mov_b32 vcc_lo, 0xaaaaaaaa
	s_mov_b32 vcc_hi, 0xaaaaaaaa
	s_nop 1
	v_cndmask_b32_dpp v109, v4, v5, vcc quad_perm:[1,0,3,2] row_mask:0xf bank_mask:0xf
	v_cndmask_b32_dpp v111, v52, v53, vcc quad_perm:[1,0,3,2] row_mask:0xf bank_mask:0xf
	v_cndmask_b32_dpp v113, v36, v37, vcc quad_perm:[1,0,3,2] row_mask:0xf bank_mask:0xf
	v_cndmask_b32_dpp v115, v20, v21, vcc quad_perm:[1,0,3,2] row_mask:0xf bank_mask:0xf
	v_pk_mul_f32 v[108:109], v[108:109], v[96:97] op_sel_hi:[1,0]
	v_pk_mul_f32 v[110:111], v[110:111], v[96:97] op_sel_hi:[1,0]
	v_pk_mul_f32 v[112:113], v[112:113], v[96:97] op_sel_hi:[1,0]
; __device__ __forceinline__ int crow(int r, int hi) { return (r & 3) + 8 * (r >> 2) + 4 * hi; }
; __device__ __forceinline__ unsigned cvtpk(float lo, float hi) { unsigned r; asm volatile("v_cvt_pk_bf16_f32 %0, %1, %2" : "=v"(r) : "v"(lo), "v"(hi)); return r; }
; template <int DKR, int LDQ, int LDK, int LDV, int LDO> ...
;     ...
;   for (int r = 0; r < 16; ++r) { int orow = crow(r, hi);
; #pragma unroll
;     for (int d0 = 0; d0 < 4; ++d0) Ow[(long)orow * LDO + d0 * 32 + r32] = (bf16_t)(cvtpk(o[d0][r] * rli[r], 0.f) & 0xffffu); }
	v_pk_mul_f32 v[114:115], v[114:115], v[96:97] op_sel_hi:[1,0]
	v_cvt_pk_bf16_f32 v73, v108, v109
	v_cvt_pk_bf16_f32 v116, v110, v111
	v_cvt_pk_bf16_f32 v117, v112, v113
	v_cvt_pk_bf16_f32 v118, v114, v115
	global_store_dword v[88:89], v73, off offset:2048
	global_store_dword v[88:89], v116, off offset:2112
	global_store_dword v[88:89], v117, off offset:2176
	global_store_dword v[88:89], v118, off offset:2240
	s_mov_b64 s[0:1], 0xa000
	v_lshl_add_u64 v[88:89], v[86:87], 0, s[0:1]
	s_mov_b32 vcc_lo, 0x55555555
	s_mov_b32 vcc_hi, 0x55555555
	s_nop 1
	v_cndmask_b32_dpp v108, v7, v6, vcc quad_perm:[1,0,3,2] row_mask:0xf bank_mask:0xf
	v_cndmask_b32_dpp v110, v55, v54, vcc quad_perm:[1,0,3,2] row_mask:0xf bank_mask:0xf
	v_cndmask_b32_dpp v112, v39, v38, vcc quad_perm:[1,0,3,2] row_mask:0xf bank_mask:0xf
	v_cndmask_b32_dpp v114, v23, v22, vcc quad_perm:[1,0,3,2] row_mask:0xf bank_mask:0xf
	s_mov_b32 vcc_lo, 0xaaaaaaaa
	s_mov_b32 vcc_hi, 0xaaaaaaaa
	s_nop 1
	v_cndmask_b32_dpp v109, v6, v7, vcc quad_perm:[1,0,3,2] row_mask:0xf bank_mask:0xf
	v_cndmask_b32_dpp v111, v54, v55, vcc quad_perm:[1,0,3,2] row_mask:0xf bank_mask:0xf
	v_cndmask_b32_dpp v113, v38, v39, vcc quad_perm:[1,0,3,2] row_mask:0xf bank_mask:0xf
	v_cndmask_b32_dpp v115, v22, v23, vcc quad_perm:[1,0,3,2] row_mask:0xf bank_mask:0xf
	v_pk_mul_f32 v[108:109], v[108:109], v[98:99] op_sel_hi:[1,0]
	v_pk_mul_f32 v[110:111], v[110:111], v[98:99] op_sel_hi:[1,0]
	v_pk_mul_f32 v[112:113], v[112:113], v[98:99] op_sel_hi:[1,0]
	v_pk_mul_f32 v[114:115], v[114:115], v[98:99] op_sel_hi:[1,0]
	v_cvt_pk_bf16_f32 v73, v108, v109
	v_cvt_pk_bf16_f32 v116, v110, v111
	v_cvt_pk_bf16_f32 v117, v112, v113
	v_cvt_pk_bf16_f32 v118, v114, v115
	global_store_dword v[88:89], v73, off offset:2048
	global_store_dword v[88:89], v116, off offset:2112
	global_store_dword v[88:89], v117, off offset:2176
	global_store_dword v[88:89], v118, off offset:2240
	s_mov_b64 s[0:1], 0x10000
	v_lshl_add_u64 v[88:89], v[86:87], 0, s[0:1]
	s_mov_b32 vcc_lo, 0x55555555
	s_mov_b32 vcc_hi, 0x55555555
	s_nop 1
	v_cndmask_b32_dpp v108, v9, v8, vcc quad_perm:[1,0,3,2] row_mask:0xf bank_mask:0xf
	v_cndmask_b32_dpp v110, v57, v56, vcc quad_perm:[1,0,3,2] row_mask:0xf bank_mask:0xf
	v_cndmask_b32_dpp v112, v41, v40, vcc quad_perm:[1,0,3,2] row_mask:0xf bank_mask:0xf
	v_cndmask_b32_dpp v114, v25, v24, vcc quad_perm:[1,0,3,2] row_mask:0xf bank_mask:0xf
	s_mov_b32 vcc_lo, 0xaaaaaaaa
	s_mov_b32 vcc_hi, 0xaaaaaaaa
	s_nop 1
	v_cndmask_b32_dpp v109, v8, v9, vcc quad_perm:[1,0,3,2] row_mask:0xf bank_mask:0xf
	v_cndmask_b32_dpp v111, v56, v57, vcc quad_perm:[1,0,3,2] row_mask:0xf bank_mask:0xf
	v_cndmask_b32_dpp v113, v40, v41, vcc quad_perm:[1,0,3,2] row_mask:0xf bank_mask:0xf
	v_cndmask_b32_dpp v115, v24, v25, vcc quad_perm:[1,0,3,2] row_mask:0xf bank_mask:0xf
	v_pk_mul_f32 v[108:109], v[108:109], v[100:101] op_sel_hi:[1,0]
	v_pk_mul_f32 v[110:111], v[110:111], v[100:101] op_sel_hi:[1,0]
	v_pk_mul_f32 v[112:113], v[112:113], v[100:101] op_sel_hi:[1,0]
	v_pk_mul_f32 v[114:115], v[114:115], v[100:101] op_sel_hi:[1,0]
	v_cvt_pk_bf16_f32 v73, v108, v109
	v_cvt_pk_bf16_f32 v116, v110, v111
	v_cvt_pk_bf16_f32 v117, v112, v113
	v_cvt_pk_bf16_f32 v118, v114, v115
	global_store_dword v[88:89], v73, off offset:2048
	global_store_dword v[88:89], v116, off offset:2112
	global_store_dword v[88:89], v117, off offset:2176
	global_store_dword v[88:89], v118, off offset:2240
	s_mov_b64 s[0:1], 0x12000
	v_lshl_add_u64 v[88:89], v[86:87], 0, s[0:1]
	s_mov_b32 vcc_lo, 0x55555555
	s_mov_b32 vcc_hi, 0x55555555
	s_nop 1
	v_cndmask_b32_dpp v108, v11, v10, vcc quad_perm:[1,0,3,2] row_mask:0xf bank_mask:0xf
	v_cndmask_b32_dpp v110, v59, v58, vcc quad_perm:[1,0,3,2] row_mask:0xf bank_mask:0xf
	v_cndmask_b32_dpp v112, v43, v42, vcc quad_perm:[1,0,3,2] row_mask:0xf bank_mask:0xf
	v_cndmask_b32_dpp v114, v27, v26, vcc quad_perm:[1,0,3,2] row_mask:0xf bank_mask:0xf
	s_mov_b32 vcc_lo, 0xaaaaaaaa
	s_mov_b32 vcc_hi, 0xaaaaaaaa
	s_nop 1
	v_cndmask_b32_dpp v109, v10, v11, vcc quad_perm:[1,0,3,2] row_mask:0xf bank_mask:0xf
; __device__ __forceinline__ int crow(int r, int hi) { return (r & 3) + 8 * (r >> 2) + 4 * hi; }
; __device__ __forceinline__ unsigned cvtpk(float lo, float hi) { unsigned r; asm volatile("v_cvt_pk_bf16_f32 %0, %1, %2" : "=v"(r) : "v"(lo), "v"(hi)); return r; }
; template <int DKR, int LDQ, int LDK, int LDV, int LDO> ...
;     ...
;   for (int r = 0; r < 16; ++r) { int orow = crow(r, hi);
; #pragma unroll
;     for (int d0 = 0; d0 < 4; ++d0) Ow[(long)orow * LDO + d0 * 32 + r32] = (bf16_t)(cvtpk(o[d0][r] * rli[r], 0.f) & 0xffffu); }
;   __syncthreads();
	v_cndmask_b32_dpp v111, v58, v59, vcc quad_perm:[1,0,3,2] row_mask:0xf bank_mask:0xf
	v_cndmask_b32_dpp v113, v42, v43, vcc quad_perm:[1,0,3,2] row_mask:0xf bank_mask:0xf
	v_cndmask_b32_dpp v115, v26, v27, vcc quad_perm:[1,0,3,2] row_mask:0xf bank_mask:0xf
	v_pk_mul_f32 v[108:109], v[108:109], v[102:103] op_sel_hi:[1,0]
	v_pk_mul_f32 v[110:111], v[110:111], v[102:103] op_sel_hi:[1,0]
	v_pk_mul_f32 v[112:113], v[112:113], v[102:103] op_sel_hi:[1,0]
	v_pk_mul_f32 v[114:115], v[114:115], v[102:103] op_sel_hi:[1,0]
	v_cvt_pk_bf16_f32 v73, v108, v109
	v_cvt_pk_bf16_f32 v116, v110, v111
	v_cvt_pk_bf16_f32 v117, v112, v113
	v_cvt_pk_bf16_f32 v118, v114, v115
	global_store_dword v[88:89], v73, off offset:2048
	global_store_dword v[88:89], v116, off offset:2112
	global_store_dword v[88:89], v117, off offset:2176
	global_store_dword v[88:89], v118, off offset:2240
	s_mov_b64 s[0:1], 0x18000
	v_lshl_add_u64 v[88:89], v[86:87], 0, s[0:1]
	s_mov_b32 vcc_lo, 0x55555555
	s_mov_b32 vcc_hi, 0x55555555
	s_nop 1
	v_cndmask_b32_dpp v108, v13, v12, vcc quad_perm:[1,0,3,2] row_mask:0xf bank_mask:0xf
	v_cndmask_b32_dpp v110, v61, v60, vcc quad_perm:[1,0,3,2] row_mask:0xf bank_mask:0xf
	v_cndmask_b32_dpp v112, v45, v44, vcc quad_perm:[1,0,3,2] row_mask:0xf bank_mask:0xf
	v_cndmask_b32_dpp v114, v29, v28, vcc quad_perm:[1,0,3,2] row_mask:0xf bank_mask:0xf
	s_mov_b32 vcc_lo, 0xaaaaaaaa
	s_mov_b32 vcc_hi, 0xaaaaaaaa
	s_nop 1
	v_cndmask_b32_dpp v109, v12, v13, vcc quad_perm:[1,0,3,2] row_mask:0xf bank_mask:0xf
	v_cndmask_b32_dpp v111, v60, v61, vcc quad_perm:[1,0,3,2] row_mask:0xf bank_mask:0xf
	v_cndmask_b32_dpp v113, v44, v45, vcc quad_perm:[1,0,3,2] row_mask:0xf bank_mask:0xf
	v_cndmask_b32_dpp v115, v28, v29, vcc quad_perm:[1,0,3,2] row_mask:0xf bank_mask:0xf
	v_pk_mul_f32 v[108:109], v[108:109], v[104:105] op_sel_hi:[1,0]
	v_pk_mul_f32 v[110:111], v[110:111], v[104:105] op_sel_hi:[1,0]
	v_pk_mul_f32 v[112:113], v[112:113], v[104:105] op_sel_hi:[1,0]
	v_pk_mul_f32 v[114:115], v[114:115], v[104:105] op_sel_hi:[1,0]
	v_cvt_pk_bf16_f32 v73, v108, v109
	v_cvt_pk_bf16_f32 v116, v110, v111
	v_cvt_pk_bf16_f32 v117, v112, v113
	v_cvt_pk_bf16_f32 v118, v114, v115
	global_store_dword v[88:89], v73, off offset:2048
	global_store_dword v[88:89], v116, off offset:2112
	global_store_dword v[88:89], v117, off offset:2176
	global_store_dword v[88:89], v118, off offset:2240
	s_mov_b64 s[0:1], 0x1a000
	v_lshl_add_u64 v[88:89], v[86:87], 0, s[0:1]
	s_mov_b32 vcc_lo, 0x55555555
	s_mov_b32 vcc_hi, 0x55555555
	s_nop 1
	v_cndmask_b32_dpp v108, v15, v14, vcc quad_perm:[1,0,3,2] row_mask:0xf bank_mask:0xf
	v_cndmask_b32_dpp v110, v63, v62, vcc quad_perm:[1,0,3,2] row_mask:0xf bank_mask:0xf
	v_cndmask_b32_dpp v112, v47, v46, vcc quad_perm:[1,0,3,2] row_mask:0xf bank_mask:0xf
	v_cndmask_b32_dpp v114, v31, v30, vcc quad_perm:[1,0,3,2] row_mask:0xf bank_mask:0xf
	s_mov_b32 vcc_lo, 0xaaaaaaaa
	s_mov_b32 vcc_hi, 0xaaaaaaaa
	s_nop 1
	v_cndmask_b32_dpp v109, v14, v15, vcc quad_perm:[1,0,3,2] row_mask:0xf bank_mask:0xf
	v_cndmask_b32_dpp v111, v62, v63, vcc quad_perm:[1,0,3,2] row_mask:0xf bank_mask:0xf
	v_cndmask_b32_dpp v113, v46, v47, vcc quad_perm:[1,0,3,2] row_mask:0xf bank_mask:0xf
	v_cndmask_b32_dpp v115, v30, v31, vcc quad_perm:[1,0,3,2] row_mask:0xf bank_mask:0xf
	v_pk_mul_f32 v[108:109], v[108:109], v[106:107] op_sel_hi:[1,0]
	v_pk_mul_f32 v[110:111], v[110:111], v[106:107] op_sel_hi:[1,0]
	v_pk_mul_f32 v[112:113], v[112:113], v[106:107] op_sel_hi:[1,0]
	v_pk_mul_f32 v[114:115], v[114:115], v[106:107] op_sel_hi:[1,0]
	v_cvt_pk_bf16_f32 v73, v108, v109
	v_cvt_pk_bf16_f32 v116, v110, v111
	v_cvt_pk_bf16_f32 v117, v112, v113
	v_cvt_pk_bf16_f32 v118, v114, v115
	global_store_dword v[88:89], v73, off offset:2048
	global_store_dword v[88:89], v116, off offset:2112
	global_store_dword v[88:89], v117, off offset:2176
	global_store_dword v[88:89], v118, off offset:2240
	s_mov_b32 s2, 4
	s_mov_b64 s[0:1], 0
	s_nop 1
	s_nop 1
	s_and_b64 vcc, exec, s[10:11]
	s_waitcnt vmcnt(63) expcnt(7) lgkmcnt(15)
	s_barrier
	s_cbranch_vccnz .LBB0_634
	s_nop 0
	s_nop 0
	s_nop 0
	s_nop 0
	s_nop 0

; #define SBAR() __builtin_amdgcn_sched_barrier(0)
; __device__ __forceinline__ void finishSM(f32x16& p0, f32x16& p1, float alpha, float& l_reg, bf16x8& pa0, bf16x8& pa1, bf16x8& pa2, bf16x8& pa3) {
; #pragma unroll
;   for (int r = 0; r < 16; ++r) p1[r] = __builtin_amdgcn_exp2f(p1[r]);
;   float ps = 0;
; #pragma unroll
;   for (int r = 0; r < 16; ++r) ps += p0[r];
; #pragma unroll
;   for (int r = 0; r < 16; ++r) ps += p1[r];
;   { auto rr = __builtin_amdgcn_permlane32_swap(__float_as_uint(ps), __float_as_uint(ps), false, false);
;     ps = __uint_as_float(rr[0]) + __uint_as_float(rr[1]); }
;   l_reg = l_reg * alpha + ps;
;     ...
;   PK4(p0, 0, pa0); PK4(p0, 8, pa1); PK4(p1, 0, pa2); PK4(p1, 8, pa3);
;     ...
; }
; template <int DKR, int NQ>
; __device__ __forceinline__ void qkt(f32x16& p0, f32x16& p1, const char* Ks, const char* Krs, const char* Qrs, const bf16x8* qr, int r32, int hi, int lane) {
;   p0 = f32x16{}; p1 = f32x16{};
; #pragma unroll
;   for (int d0 = 0; d0 < 8; ++d0) { int cb = (d0 * 16 + hi * 8) * 2;
;     bf16x8 b0 = *reinterpret_cast<const bf16x8*>(Ks + KSWZ(r32, cb));
;     bf16x8 b1 = *reinterpret_cast<const bf16x8*>(Ks + KSWZ(32 + r32, cb));
;     bf16x8 qf;
;     if (d0 >= 8 - NQ) qf = *reinterpret_cast<const bf16x8*>(Qrs + (d0 - (8 - NQ) + 4) * 1024 + lane * 16); else qf = qr[d0];
;     p0 = __builtin_amdgcn_mfma_f32_32x32x16_bf16(b0, qf, p0, 0, 0, 0);
;     p1 = __builtin_amdgcn_mfma_f32_32x32x16_bf16(b1, qf, p1, 0, 0, 0); }
; template <int DKR, int LDQ, int LDK, int LDV, int LDO> ...
;     ...
;     SLOAD(SO, (j + SD) * KVBLK); SBAR();
;     pv_sm(o, vb0, pa0, pa1, pa2, pa3, pB0, pB1, m_reg, mnB, alB, SCALE);
.LBB0_616:
	ds_read_b128 v[64:67], v194 offset:49152
	ds_read_b128 v[68:71], v194 offset:57344
	ds_read_b128 v[204:207], v200 offset:49152
	ds_read_b128 v[208:211], v200 offset:57344
	v_exp_f32_e32 v156, v156
	v_exp_f32_e32 v157, v157
	s_waitcnt lgkmcnt(3)
	v_mfma_f32_32x32x16_bf16 v[80:95], v[64:67], v[124:127], 0
	v_exp_f32_e32 v154, v154
	v_exp_f32_e32 v155, v155
	v_exp_f32_e32 v148, v148
	v_exp_f32_e32 v149, v149
	v_exp_f32_e32 v146, v146
	v_exp_f32_e32 v147, v147
	v_exp_f32_e32 v144, v144
	s_waitcnt lgkmcnt(2)
	v_mfma_f32_32x32x16_bf16 v[64:79], v[68:71], v[124:127], 0
	v_exp_f32_e32 v145, v145
	v_exp_f32_e32 v158, v158
	v_exp_f32_e32 v159, v159
	v_exp_f32_e32 v152, v152
	v_exp_f32_e32 v153, v153
	v_exp_f32_e32 v150, v150
	v_exp_f32_e32 v151, v151
	s_waitcnt lgkmcnt(1)
	v_mfma_f32_32x32x16_bf16 v[80:95], v[204:207], v[120:123], v[80:95]
	s_waitcnt lgkmcnt(0)
	v_mfma_f32_32x32x16_bf16 v[64:79], v[208:211], v[120:123], v[64:79]
	ds_read_b128 v[204:207], v201 offset:49152
	ds_read_b128 v[208:211], v201 offset:57344
	s_waitcnt lgkmcnt(1)
	v_mfma_f32_32x32x16_bf16 v[80:95], v[204:207], v[116:119], v[80:95]
	s_waitcnt lgkmcnt(0)
	v_mfma_f32_32x32x16_bf16 v[64:79], v[208:211], v[116:119], v[64:79]
	ds_read_b128 v[204:207], v195 offset:49152
	ds_read_b128 v[208:211], v195 offset:57344
	s_waitcnt lgkmcnt(1)
	v_mfma_f32_32x32x16_bf16 v[80:95], v[204:207], v[112:115], v[80:95]
	s_waitcnt lgkmcnt(0)
	v_mfma_f32_32x32x16_bf16 v[64:79], v[208:211], v[112:115], v[64:79]
	ds_read_b128 v[204:207], v196 offset:49152
	ds_read_b128 v[208:211], v196 offset:57344
	s_waitcnt lgkmcnt(1)
	v_mfma_f32_32x32x16_bf16 v[80:95], v[204:207], v[108:111], v[80:95]
	s_waitcnt lgkmcnt(0)
	v_mfma_f32_32x32x16_bf16 v[64:79], v[208:211], v[108:111], v[64:79]
	ds_read_b128 v[204:207], v197 offset:49152
	ds_read_b128 v[208:211], v197 offset:57344
	s_waitcnt lgkmcnt(1)
	v_mfma_f32_32x32x16_bf16 v[80:95], v[204:207], v[104:107], v[80:95]
	s_waitcnt lgkmcnt(0)
	v_mfma_f32_32x32x16_bf16 v[64:79], v[208:211], v[104:107], v[64:79]
	ds_read_b128 v[204:207], v198 offset:49152
	ds_read_b128 v[208:211], v198 offset:57344
	s_waitcnt lgkmcnt(1)
	v_mfma_f32_32x32x16_bf16 v[80:95], v[204:207], v[100:103], v[80:95]
	s_waitcnt lgkmcnt(0)
	v_mfma_f32_32x32x16_bf16 v[64:79], v[208:211], v[100:103], v[64:79]
	ds_read_b128 v[204:207], v199 offset:49152
	ds_read_b128 v[208:211], v199 offset:57344
	s_waitcnt lgkmcnt(1)
	v_mfma_f32_32x32x16_bf16 v[80:95], v[204:207], v[96:99], v[80:95]
	v_add_f32_e32 v204, 0, v160
	v_add_f32_e32 v204, v175, v204
	v_add_f32_e32 v204, v161, v204
	v_add_f32_e32 v204, v174, v204
	v_add_f32_e32 v204, v162, v204
	v_add_f32_e32 v204, v173, v204
	v_add_f32_e32 v204, v163, v204
	v_add_f32_e32 v204, v172, v204
	v_add_f32_e32 v204, v164, v204
	v_add_f32_e32 v204, v171, v204
	v_add_f32_e32 v204, v165, v204
	v_add_f32_e32 v204, v170, v204
	v_add_f32_e32 v204, v166, v204
	v_add_f32_e32 v204, v169, v204
	v_add_f32_e32 v204, v167, v204
	v_add_f32_e32 v204, v168, v204
	v_add_f32_e32 v204, v156, v204
	v_add_f32_e32 v204, v157, v204
	v_add_f32_e32 v204, v154, v204
	v_add_f32_e32 v204, v155, v204
	v_add_f32_e32 v204, v148, v204
	v_add_f32_e32 v204, v149, v204
	v_add_f32_e32 v204, v146, v204
	v_add_f32_e32 v204, v147, v204
	v_add_f32_e32 v204, v144, v204
	v_add_f32_e32 v204, v145, v204
	s_waitcnt lgkmcnt(0)
	v_mfma_f32_32x32x16_bf16 v[64:79], v[208:211], v[96:99], v[64:79]
	v_add_f32_e32 v204, v158, v204
	v_add_f32_e32 v204, v159, v204
	v_add_f32_e32 v204, v152, v204
	v_add_f32_e32 v204, v153, v204
	v_add_f32_e32 v204, v150, v204
	v_add_f32_e32 v205, v151, v204
	v_mov_b32_e32 v206, v205
	s_nop 1
	v_permlane32_swap_b32_e32 v205, v206
	v_cvt_pk_bf16_f32 v160, v160, v175
	v_cvt_pk_bf16_f32 v161, v161, v174
	v_cvt_pk_bf16_f32 v162, v162, v173
	v_cvt_pk_bf16_f32 v163, v163, v172
	v_cvt_pk_bf16_f32 v164, v164, v171
	v_cvt_pk_bf16_f32 v165, v165, v170
	v_cvt_pk_bf16_f32 v166, v166, v169
	v_cvt_pk_bf16_f32 v167, v167, v168
	v_cvt_pk_bf16_f32 v168, v156, v157
	v_cvt_pk_bf16_f32 v169, v154, v155
	v_cvt_pk_bf16_f32 v170, v148, v149
	v_cvt_pk_bf16_f32 v171, v146, v147
	v_cvt_pk_bf16_f32 v172, v144, v145
	v_cvt_pk_bf16_f32 v173, v158, v159
	v_cvt_pk_bf16_f32 v174, v152, v153
	v_cvt_pk_bf16_f32 v175, v150, v151
	s_nop 0
	v_permlane32_swap_b32_e32 v160, v162
	v_permlane32_swap_b32_e32 v161, v163
	v_permlane32_swap_b32_e32 v164, v166
	v_permlane32_swap_b32_e32 v165, v167
	v_permlane32_swap_b32_e32 v168, v170
	v_permlane32_swap_b32_e32 v169, v171
	v_permlane32_swap_b32_e32 v172, v174
	v_permlane32_swap_b32_e32 v173, v175
	s_mov_b32 s0, 0xffff4000
	v_add_co_u32_e32 v144, vcc, s0, v180
	s_movk_i32 s0, 0x8000
	s_nop 0
	v_addc_co_u32_e32 v145, vcc, -1, v181, vcc
	v_add_co_u32_e32 v148, vcc, s0, v180
	s_mov_b32 s0, 0xff6f4000
	s_nop 0
	v_addc_co_u32_e32 v149, vcc, -1, v181, vcc
	v_add_co_u32_e32 v152, vcc, s0, v180
	s_mov_b32 s0, 0xff6f8000
	s_nop 0
	v_addc_co_u32_e32 v153, vcc, -1, v181, vcc
	v_add_co_u32_e32 v156, vcc, s0, v180
	global_load_dwordx4 v[144:147], v[144:145], off
	s_nop 0
	global_load_dwordx4 v[148:151], v[148:149], off
	v_addc_co_u32_e32 v157, vcc, -1, v181, vcc
	global_load_dwordx4 v[152:155], v[152:153], off
	s_nop 0
	global_load_dwordx4 v[156:159], v[156:157], off
	ds_read_b64_tr_b16 v[208:209], v188 offset:0
	ds_read_b64_tr_b16 v[210:211], v188 offset:0x800
	ds_read_b64_tr_b16 v[214:215], v188 offset:0x1000
	ds_read_b64_tr_b16 v[216:217], v188 offset:0x1800
	ds_read_b64_tr_b16 v[218:219], v188 offset:0x2000
	ds_read_b64_tr_b16 v[220:221], v188 offset:0x2800
	ds_read_b64_tr_b16 v[222:223], v188 offset:0x3000
	ds_read_b64_tr_b16 v[224:225], v188 offset:0x3800
	s_nop 0
	s_waitcnt lgkmcnt(6)
; template <int D0> __device__ __forceinline__ void pv_one(f32x16& od, int vb, bf16x8 pa0, bf16x8 pa1, bf16x8 pa2, bf16x8 pa3) {
;   const s16x4 l0 = tr_read<v_rd_off(D0, 0, 0)>(vb), h0 = tr_read<v_rd_off(D0, 0, 1)>(vb), l1 = tr_read<v_rd_off(D0, 1, 0)>(vb), h1 = tr_read<v_rd_off(D0, 1, 1)>(vb);
;   const s16x4 l2 = tr_read<v_rd_off(D0, 2, 0)>(vb), h2 = tr_read<v_rd_off(D0, 2, 1)>(vb), l3 = tr_read<v_rd_off(D0, 3, 0)>(vb), h3 = tr_read<v_rd_off(D0, 3, 1)>(vb);
;   asm volatile("s_waitcnt lgkmcnt(0)" ::: "memory"); SBAR();
;     ...
;   od = __builtin_amdgcn_mfma_f32_32x32x16_bf16(pa0, PK(l0, h0), od, 0, 0, 0);
;   od = __builtin_amdgcn_mfma_f32_32x32x16_bf16(pa1, PK(l1, h1), od, 0, 0, 0);
;   od = __builtin_amdgcn_mfma_f32_32x32x16_bf16(pa2, PK(l2, h2), od, 0, 0, 0);
;   od = __builtin_amdgcn_mfma_f32_32x32x16_bf16(pa3, PK(l3, h3), od, 0, 0, 0);
;     ...
; }
; __device__ __forceinline__ void pv_d0(f32x16* o, int vb, bf16x8 pa0, bf16x8 pa1, bf16x8 pa2, bf16x8 pa3) {
;   pv_one<0>(o[0], vb, pa0, pa1, pa2, pa3); pv_one<1>(o[1], vb, pa0, pa1, pa2, pa3); pv_one<2>(o[2], vb, pa0, pa1, pa2, pa3); pv_one<3>(o[3], vb, pa0, pa1, pa2, pa3);
; }
; __device__ __forceinline__ void pv_sm(f32x16* o, int vb, bf16x8 pa0, bf16x8 pa1, bf16x8 pa2, bf16x8 pa3, f32x16& p0, f32x16& p1, float& m_reg, float& mn, float& alpha, const float SCALE) {
;   const float C = SCALE * 1.4426950408889634f;
;   pv_one<0>(o[0], vb, pa0, pa1, pa2, pa3);
;   float pmax = p0[0];
; #pragma unroll
;   for (int r = 1; r < 16; ++r) pmax = fmaxf(pmax, p0[r]);
;   pv_one<1>(o[1], vb, pa0, pa1, pa2, pa3);
; #pragma unroll
;   for (int r = 0; r < 16; ++r) pmax = fmaxf(pmax, p1[r]);
;   { auto rr = __builtin_amdgcn_permlane32_swap(__float_as_uint(pmax), __float_as_uint(pmax), false, false);
;     pmax = fmaxf(__uint_as_float(rr[0]), __uint_as_float(rr[1])); }
;   if (__builtin_expect(__all(pmax - m_reg <= THR / SCALE), 1)) { mn = m_reg; alpha = 1.f; }
;   else { mn = fmaxf(m_reg, pmax); alpha = __builtin_amdgcn_exp2f((m_reg - mn) * C); m_reg = mn; }
;   const float mnC = -mn * C;
;   pv_one<2>(o[2], vb, pa0, pa1, pa2, pa3);
; #pragma unroll
;   for (int r = 0; r < 16; ++r) p0[r] = fmaf(p0[r], C, mnC);
; #pragma unroll
;   for (int r = 0; r < 16; ++r) p1[r] = fmaf(p1[r], C, mnC);
;   pv_one<3>(o[3], vb, pa0, pa1, pa2, pa3);
; #pragma unroll
;   for (int r = 0; r < 16; ++r) p0[r] = __builtin_amdgcn_exp2f(p0[r]);
; }
	v_mfma_f32_32x32x16_bf16 v[0:15], v[160:163], v[208:211], v[0:15]
	ds_read_b64_tr_b16 v[208:209], v188 offset:0x200
	ds_read_b64_tr_b16 v[210:211], v188 offset:0xa00
	v_max_f32_e32 v204, v81, v81
	v_max_f32_e32 v207, v80, v80
	v_max_f32_e32 v204, v207, v204
	v_max3_f32 v204, v204, v82, v83
	v_max3_f32 v204, v204, v84, v85
	s_waitcnt lgkmcnt(6)
	v_mfma_f32_32x32x16_bf16 v[0:15], v[164:167], v[214:217], v[0:15]
	ds_read_b64_tr_b16 v[214:215], v188 offset:0x1200
	ds_read_b64_tr_b16 v[216:217], v188 offset:0x1a00
	v_max3_f32 v204, v204, v86, v87
	v_max3_f32 v204, v204, v88, v89
	v_max3_f32 v204, v204, v90, v91
	v_max3_f32 v204, v204, v92, v93
	v_max3_f32 v204, v204, v94, v95
	s_waitcnt lgkmcnt(6)
	v_mfma_f32_32x32x16_bf16 v[0:15], v[168:171], v[218:221], v[0:15]
	ds_read_b64_tr_b16 v[218:219], v188 offset:0x2200
	ds_read_b64_tr_b16 v[220:221], v188 offset:0x2a00
	ds_read_b64_tr_b16 v[226:227], v188 offset:0x3200
	ds_read_b64_tr_b16 v[228:229], v188 offset:0x3a00
	s_waitcnt lgkmcnt(8)
	v_mfma_f32_32x32x16_bf16 v[0:15], v[172:175], v[222:225], v[0:15]
	s_waitcnt lgkmcnt(6)
	v_mfma_f32_32x32x16_bf16 v[48:63], v[160:163], v[208:211], v[48:63]
	v_max3_f32 v204, v204, v64, v65
	v_max3_f32 v204, v204, v66, v67
	v_max3_f32 v204, v204, v68, v69
	v_max3_f32 v204, v204, v70, v71
	v_max3_f32 v204, v204, v72, v73
	v_max3_f32 v204, v204, v74, v75
	v_max3_f32 v204, v204, v76, v77
	s_waitcnt lgkmcnt(4)
	v_mfma_f32_32x32x16_bf16 v[48:63], v[164:167], v[214:217], v[48:63]
	v_max3_f32 v204, v204, v78, v79
	v_mov_b32_e32 v207, v204
	s_nop 1
	v_permlane32_swap_b32_e32 v204, v207
	v_max_f32_e32 v207, v207, v207
	v_max_f32_e32 v204, v204, v204
	v_max_f32_e32 v204, v204, v207
	v_max_f32_e32 v208, v203, v203
	v_sub_f32_e32 v207, v204, v203
	v_max_f32_e32 v204, v208, v204
	v_sub_f32_e32 v208, v203, v204
	v_mul_f32_e32 v208, 0x3e0293ee, v208
	s_waitcnt lgkmcnt(2)
	v_mfma_f32_32x32x16_bf16 v[48:63], v[168:171], v[218:221], v[48:63]
	v_exp_f32_e32 v208, v208
	v_cmp_ge_f32_e32 vcc, s47, v207
	s_cmp_eq_u64 vcc, exec
	s_cselect_b64 s[4:5], -1, 0
	v_cndmask_b32_e64 v207, v208, 1.0, s[4:5]
	ds_read_b64_tr_b16 v[208:209], v188 offset:0x400
	ds_read_b64_tr_b16 v[210:211], v188 offset:0xc00
	ds_read_b64_tr_b16 v[214:215], v188 offset:0x1400
	s_waitcnt lgkmcnt(3)
	v_mfma_f32_32x32x16_bf16 v[48:63], v[172:175], v[226:229], v[48:63]
	ds_read_b64_tr_b16 v[216:217], v188 offset:0x1c00
	ds_read_b64_tr_b16 v[218:219], v188 offset:0x2400
	ds_read_b64_tr_b16 v[220:221], v188 offset:0x2c00
	ds_read_b64_tr_b16 v[222:223], v188 offset:0x3400
	ds_read_b64_tr_b16 v[224:225], v188 offset:0x3c00
	s_waitcnt lgkmcnt(6)
	v_mfma_f32_32x32x16_bf16 v[32:47], v[160:163], v[208:211], v[32:47]
	ds_read_b64_tr_b16 v[208:209], v188 offset:0x600
	ds_read_b64_tr_b16 v[210:211], v188 offset:0xe00
	s_waitcnt lgkmcnt(6)
	v_mfma_f32_32x32x16_bf16 v[32:47], v[164:167], v[214:217], v[32:47]
	ds_read_b64_tr_b16 v[214:215], v188 offset:0x1600
	ds_read_b64_tr_b16 v[216:217], v188 offset:0x1e00
	s_waitcnt lgkmcnt(6)
	v_mfma_f32_32x32x16_bf16 v[32:47], v[168:171], v[218:221], v[32:47]
	ds_read_b64_tr_b16 v[218:219], v188 offset:0x2600
	ds_read_b64_tr_b16 v[220:221], v188 offset:0x2e00
	ds_read_b64_tr_b16 v[226:227], v188 offset:0x3600
	ds_read_b64_tr_b16 v[228:229], v188 offset:0x3e00
	s_waitcnt lgkmcnt(8)
	v_mfma_f32_32x32x16_bf16 v[32:47], v[172:175], v[222:225], v[32:47]
	s_waitcnt lgkmcnt(6)
	v_mfma_f32_32x32x16_bf16 v[16:31], v[160:163], v[208:211], v[16:31]
	s_waitcnt lgkmcnt(0)
	s_barrier
	s_waitcnt vmcnt(4)
	v_cmp_gt_f32_e32 vcc, 1.0, v207
	s_waitcnt vmcnt(4)
	ds_write_b128 v192, v[132:135]
	ds_write_b128 v193, v[140:143]
	ds_write_b128 v190, v[128:131] offset:32768
	ds_write_b128 v191, v[136:139] offset:32768
	v_mfma_f32_32x32x16_bf16 v[16:31], v[164:167], v[214:217], v[16:31]
	v_mfma_f32_32x32x16_bf16 v[16:31], v[168:171], v[218:221], v[16:31]
	v_mfma_f32_32x32x16_bf16 v[16:31], v[172:175], v[226:229], v[16:31]
	s_cbranch_vccz .LBB0_620
	s_and_saveexec_b64 s[0:1], s[2:3]
	ds_write_b32 v185, v207 offset:128
	s_or_b64 exec, exec, s[0:1]
	s_waitcnt lgkmcnt(0)
	v_add_u32_e32 v172, v179, v176
	ds_read_b128 v[160:163], v172 offset:224
	ds_read_b128 v[164:167], v172 offset:192
	ds_read_b128 v[168:171], v172 offset:160
	ds_read_b128 v[172:175], v172 offset:128
	s_waitcnt lgkmcnt(3)
	v_pk_mul_f32 v[12:13], v[12:13], v[160:161]
	s_waitcnt lgkmcnt(2)
	v_pk_mul_f32 v[8:9], v[8:9], v[164:165]
	s_waitcnt lgkmcnt(1)
	v_pk_mul_f32 v[4:5], v[4:5], v[168:169]
	v_pk_mul_f32 v[14:15], v[14:15], v[162:163]
	v_pk_mul_f32 v[10:11], v[10:11], v[166:167]
	v_pk_mul_f32 v[6:7], v[6:7], v[170:171]
	s_waitcnt lgkmcnt(0)
	v_pk_mul_f32 v[2:3], v[2:3], v[174:175]
	v_pk_mul_f32 v[0:1], v[0:1], v[172:173]
	v_pk_mul_f32 v[60:61], v[60:61], v[160:161]
	v_pk_mul_f32 v[56:57], v[56:57], v[164:165]
	v_pk_mul_f32 v[52:53], v[52:53], v[168:169]
	v_pk_mul_f32 v[62:63], v[62:63], v[162:163]
	v_pk_mul_f32 v[58:59], v[58:59], v[166:167]
	v_pk_mul_f32 v[54:55], v[54:55], v[170:171]
	v_pk_mul_f32 v[50:51], v[50:51], v[174:175]
	v_pk_mul_f32 v[48:49], v[48:49], v[172:173]
	v_pk_mul_f32 v[44:45], v[44:45], v[160:161]
	v_pk_mul_f32 v[40:41], v[40:41], v[164:165]
	v_pk_mul_f32 v[36:37], v[36:37], v[168:169]
	v_pk_mul_f32 v[46:47], v[46:47], v[162:163]
	v_pk_mul_f32 v[42:43], v[42:43], v[166:167]
	v_pk_mul_f32 v[38:39], v[38:39], v[170:171]
	v_pk_mul_f32 v[34:35], v[34:35], v[174:175]
	v_pk_mul_f32 v[32:33], v[32:33], v[172:173]
	v_pk_mul_f32 v[28:29], v[28:29], v[160:161]
	v_pk_mul_f32 v[24:25], v[24:25], v[164:165]
	v_pk_mul_f32 v[20:21], v[20:21], v[168:169]
	v_pk_mul_f32 v[30:31], v[30:31], v[162:163]
	v_pk_mul_f32 v[26:27], v[26:27], v[166:167]
	v_pk_mul_f32 v[22:23], v[22:23], v[170:171]
	v_pk_mul_f32 v[18:19], v[18:19], v[174:175]
	v_pk_mul_f32 v[16:17], v[16:17], v[172:173]
